# P0: odd waves run rms rows first then weight conversion (even waves the original order) so both access patterns stay in flight together
# baseline (speedup 1.0000x reference)
; #define LAS __attribute__((address_space(3)))
; #define PH(k) if constexpr ((PHASE_MASK >> (k)) & 1) _Pragma("nounroll") for (int rep_ = 0; rep_ < ((((REP_MASK) >> (k)) & 1) ? 2 : 1); ++rep_)
; #define INF(k) ((const float*)LDP(k))
; __global__ void __launch_bounds__(512, 2) fwd_megakernel(Args a) {
;     ...
;     PH(0) { PH_IDS
;         LAS float* scr = (LAS float*)(lds + wave * 16384);
;         for (int it = gw; it < IT_IN + IT_GU; it += ngw) {
;             int r = it;
;     ...
;         for (int m = gw; m < T; m += ngw) rms_row_to_bf16(INF(I_X) + (size_t)m * DM, INF(I_GMIXPRE), HB + (size_t)m * DM, lane);
.LBB0_3:
	s_or_b64 exec, exec, s[22:23]
	s_add_i32 s0, 0, 0x23ce8
	v_mov_b32_e32 v1, s0
	s_waitcnt lgkmcnt(0)
	s_barrier
	ds_read_b64 v[2:3], v1
	s_andn2_b32 s84, s84, 63
	v_mbcnt_lo_u32_b32 v1, -1, 0
	v_mbcnt_hi_u32_b32 v1, -1, v1
	s_lshl_b32 s92, s33, 3
	v_add_u32_e32 v7, s84, v1
	s_lshl_b32 s50, s54, 3
	v_readfirstlane_b32 s0, v7
	s_ashr_i32 s3, s0, 6
	s_waitcnt lgkmcnt(0)
	v_readfirstlane_b32 s52, v2
	v_and_b32_e32 v2, 63, v7
	s_add_i32 s2, s3, s92
	v_readfirstlane_b32 s53, v3
	s_cmpk_lt_i32 s2, 0x5200
	v_and_b32_e32 v6, 31, v7
	v_lshlrev_b32_e32 v8, 3, v2
	s_mov_b32 s93, 0
	s_cbranch_scc0 .LBB0_20
	s_and_b32 s93, s3, 1
	s_cmp_eq_u32 s93, 0
	s_cbranch_scc0 .LBB0_20
.Lp0_conv:
	v_and_b32_e32 v1, 56, v8
	v_mov_b32_e32 v11, 0
	v_lshlrev_b32_e32 v10, 1, v1
	s_lshl_b32 s0, s3, 14
	v_lshrrev_b32_e32 v3, 3, v2
	v_lshl_add_u64 v[16:17], s[52:53], 0, v[10:11]
	s_mov_b64 s[4:5], 0x1100000
	s_add_i32 s0, s0, 0
	v_lshrrev_b32_e32 v4, 5, v2
	v_mul_u32_u24_e32 v5, 0x84, v1
	v_lshl_add_u64 v[14:15], v[16:17], 0, s[4:5]
	v_lshlrev_b32_e32 v1, 2, v3
	s_mov_b64 s[4:5], 0xa800000
	s_mov_b32 s1, 0
	v_lshl_add_u32 v12, v6, 2, s0
	s_movk_i32 s8, 0x84
	v_add3_u32 v5, s0, v5, v1
	v_or_b32_e32 v9, 8, v3
	v_or_b32_e32 v13, 16, v3
	v_or_b32_e32 v21, 24, v3
	v_lshl_add_u64 v[16:17], v[16:17], 0, s[4:5]
	v_mov_b32_e32 v1, v4
	s_add_i32 s9, 0, 0x23ca8
	s_mov_b32 s10, 0xb000
	s_movk_i32 s11, 0xe200
	s_add_i32 s12, 0, 0x23c60
	s_mov_b32 s13, 0x9800
	v_lshlrev_b32_e32 v10, 2, v6
	s_mov_b32 s14, s2
	s_branch .LBB0_6

; #define INF(k) ((const float*)LDP(k))
; __global__ void __launch_bounds__(512, 2) fwd_megakernel(Args a) {
;     ...
;         }
;         for (int m = gw; m < T; m += ngw) rms_row_to_bf16(INF(I_X) + (size_t)m * DM, INF(I_GMIXPRE), HB + (size_t)m * DM, lane);
.Lp0_conv_done:
	s_cmp_eq_u32 s93, 2
	s_cbranch_scc1 .LBB0_23

; #define INF(k) ((const float*)LDP(k))
; __global__ void __launch_bounds__(512, 2) fwd_megakernel(Args a) {
;     ...
;         for (int m = gw; m < T; m += ngw) rms_row_to_bf16(INF(I_X) + (size_t)m * DM, INF(I_GMIXPRE), HB + (size_t)m * DM, lane);
;         const int gt = bid * 512 + tid, ngt = G * 512;
.LBB0_23:
	s_cmp_eq_u32 s93, 1
	s_cbranch_scc0 .Lp0_rope
	s_mov_b32 s93, 2
	v_and_b32_e32 v2, 63, v7
	v_readfirstlane_b32 s0, v7
	v_lshlrev_b32_e32 v8, 3, v2
	s_ashr_i32 s3, s0, 6
	s_add_i32 s2, s3, s92
	s_branch .Lp0_conv
